# GEMM tile headers: accumulator clears as 64-bit moves (124 pairs) on top of v99
# baseline (speedup 1.0000x reference)
.LBB0_225:
	s_and_b32 s1, s0, 7
	s_mulk_i32 s1, 0xb4
	s_ashr_i32 s0, s0, 3
	s_add_i32 s1, s1, s0
	s_mul_hi_i32 s0, s1, 0x66666667
	s_lshr_b32 s3, s0, 31
	s_ashr_i32 s0, s0, 5
	s_add_i32 s0, s0, s3
	s_mul_i32 s3, s0, 0x50
	s_sub_i32 s1, s1, s3
	s_lshl_b32 s19, s0, 10
	s_lshl_b32 s0, s1, 7
	s_and_b32 s22, s0, 0x380
	s_lshl_b32 s3, s1, 4
	s_and_b32 s38, s3, 0xffffff80
	s_or_b32 s40, s19, s22
	s_ashr_i32 s39, s38, 31
	s_waitcnt vmcnt(16)
	s_ashr_i32 s41, s40, 31
	s_lshl_b64 s[0:1], s[38:39], 11
	s_lshl_b64 s[22:23], s[40:41], 11
	v_mov_b32_e32 v2, 0
	v_lshl_add_u64 v[66:67], v[98:99], 0, s[22:23]
	v_lshl_add_u64 v[68:69], v[100:101], 0, s[22:23]
	v_lshl_add_u64 v[70:71], v[102:103], 0, s[22:23]
	v_lshl_add_u64 v[72:73], v[104:105], 0, s[22:23]
	v_lshl_add_u64 v[74:75], v[106:107], 0, s[0:1]
	v_lshl_add_u64 v[76:77], v[108:109], 0, s[0:1]
	v_lshl_add_u64 v[78:79], v[110:111], 0, s[0:1]
	v_lshl_add_u64 v[80:81], v[112:113], 0, s[0:1]
	s_mov_b32 s19, 0
	v_mov_b32_e32 v3, v2
	v_mov_b64_e32 v[4:5], v[2:3]
	v_mov_b64_e32 v[6:7], v[2:3]
	v_mov_b64_e32 v[8:9], v[2:3]
	v_mov_b64_e32 v[10:11], v[2:3]
	v_mov_b64_e32 v[12:13], v[2:3]
	v_mov_b64_e32 v[14:15], v[2:3]
	v_mov_b64_e32 v[16:17], v[2:3]
	v_mov_b64_e32 v[18:19], v[2:3]
	v_mov_b64_e32 v[20:21], v[2:3]
	v_mov_b64_e32 v[22:23], v[2:3]
	v_mov_b64_e32 v[24:25], v[2:3]
	v_mov_b64_e32 v[26:27], v[2:3]
	v_mov_b64_e32 v[28:29], v[2:3]
	v_mov_b64_e32 v[30:31], v[2:3]
	v_mov_b64_e32 v[32:33], v[2:3]
	v_mov_b64_e32 v[34:35], v[2:3]
	v_mov_b64_e32 v[36:37], v[2:3]
	v_mov_b64_e32 v[38:39], v[2:3]
	v_mov_b64_e32 v[40:41], v[2:3]
	v_mov_b64_e32 v[42:43], v[2:3]
	v_mov_b64_e32 v[44:45], v[2:3]
	v_mov_b64_e32 v[46:47], v[2:3]
	v_mov_b64_e32 v[48:49], v[2:3]
	v_mov_b64_e32 v[50:51], v[2:3]
	v_mov_b64_e32 v[52:53], v[2:3]
	v_mov_b64_e32 v[54:55], v[2:3]
	v_mov_b64_e32 v[56:57], v[2:3]
	v_mov_b64_e32 v[58:59], v[2:3]
	v_mov_b64_e32 v[60:61], v[2:3]
	v_mov_b64_e32 v[62:63], v[2:3]
	v_mov_b64_e32 v[64:65], v[2:3]
	v_and_b32_e32 v214, 63, v188
	v_lshrrev_b32_e32 v215, 3, v214
	v_and_b32_e32 v216, 7, v214
	v_xor_b32_e32 v216, v216, v215
	v_mul_u32_u24_e32 v246, 0x800, v215
	v_lshl_add_u32 v246, v216, 4, v246
	v_add_u32_e32 v247, 0x4000, v246
	v_add_u32_e32 v248, 0x8000, v246
	v_add_u32_e32 v249, 0xc000, v246
	v_lshrrev_b32_e32 v250, 6, v188
	v_lshlrev_b32_e32 v250, 12, v250
	v_readfirstlane_b32 s98, v66
	v_readfirstlane_b32 s99, v67
	v_readfirstlane_b32 s100, v74
	v_readfirstlane_b32 s101, v75
	s_add_u32 s98, s98, s44
	s_addc_u32 s99, s99, s45
	s_add_u32 s100, s100, s44
	s_addc_u32 s101, s101, s45
	s_waitcnt vmcnt(16) lgkmcnt(0)
	s_barrier

.LBB0_891:
	s_and_b32 s1, s0, 7
	s_mul_i32 s1, s1, s2
	s_ashr_i32 s0, s0, 3
	s_add_i32 s0, s1, s0
	s_ashr_i32 s1, s0, 31
	s_lshr_b32 s1, s1, 26
	s_add_i32 s1, s0, s1
	s_and_b32 s19, s1, 0xffffffc0
	s_sub_i32 s0, s0, s19
	s_lshl_b32 s1, s1, 4
	s_and_b32 s19, s1, 0xfffffc00
	s_lshl_b32 s1, s0, 7
	s_and_b32 s26, s1, 0x380
	s_lshl_b32 s0, s0, 4
	s_and_b32 s42, s0, 0xffffff80
	s_or_b32 s40, s19, s26
	s_ashr_i32 s43, s42, 31
	s_waitcnt vmcnt(16)
	s_ashr_i32 s41, s40, 31
	s_lshl_b64 s[0:1], s[42:43], 11
	s_lshl_b64 s[26:27], s[40:41], 11
	v_mov_b32_e32 v2, 0
	v_lshl_add_u64 v[96:97], v[70:71], 0, s[26:27]
	v_lshl_add_u64 v[98:99], v[72:73], 0, s[26:27]
	v_lshl_add_u64 v[100:101], v[74:75], 0, s[26:27]
	v_lshl_add_u64 v[102:103], v[76:77], 0, s[26:27]
	v_lshl_add_u64 v[104:105], v[78:79], 0, s[0:1]
	v_lshl_add_u64 v[106:107], v[80:81], 0, s[0:1]
	v_lshl_add_u64 v[108:109], v[82:83], 0, s[0:1]
	v_lshl_add_u64 v[110:111], v[84:85], 0, s[0:1]
	s_mov_b32 s19, 0
	v_mov_b32_e32 v3, v2
	v_mov_b64_e32 v[4:5], v[2:3]
	v_mov_b64_e32 v[6:7], v[2:3]
	v_mov_b64_e32 v[8:9], v[2:3]
	v_mov_b64_e32 v[10:11], v[2:3]
	v_mov_b64_e32 v[12:13], v[2:3]
	v_mov_b64_e32 v[14:15], v[2:3]
	v_mov_b64_e32 v[16:17], v[2:3]
	v_mov_b64_e32 v[18:19], v[2:3]
	v_mov_b64_e32 v[20:21], v[2:3]
	v_mov_b64_e32 v[22:23], v[2:3]
	v_mov_b64_e32 v[24:25], v[2:3]
	v_mov_b64_e32 v[26:27], v[2:3]
	v_mov_b64_e32 v[28:29], v[2:3]
	v_mov_b64_e32 v[30:31], v[2:3]
	v_mov_b64_e32 v[32:33], v[2:3]
	v_mov_b64_e32 v[34:35], v[2:3]
	v_mov_b64_e32 v[36:37], v[2:3]
	v_mov_b64_e32 v[38:39], v[2:3]
	v_mov_b64_e32 v[40:41], v[2:3]
	v_mov_b64_e32 v[42:43], v[2:3]
	v_mov_b64_e32 v[44:45], v[2:3]
	v_mov_b64_e32 v[46:47], v[2:3]
	v_mov_b64_e32 v[48:49], v[2:3]
	v_mov_b64_e32 v[50:51], v[2:3]
	v_mov_b64_e32 v[52:53], v[2:3]
	v_mov_b64_e32 v[54:55], v[2:3]
	v_mov_b64_e32 v[56:57], v[2:3]
	v_mov_b64_e32 v[58:59], v[2:3]
	v_mov_b64_e32 v[60:61], v[2:3]
	v_mov_b64_e32 v[62:63], v[2:3]
	v_mov_b64_e32 v[64:65], v[2:3]
	v_and_b32_e32 v214, 63, v188
	v_lshrrev_b32_e32 v215, 3, v214
	v_and_b32_e32 v216, 7, v214
	v_xor_b32_e32 v216, v216, v215
	v_mul_u32_u24_e32 v246, 0x800, v215
	v_lshl_add_u32 v246, v216, 4, v246
	v_add_u32_e32 v247, 0x4000, v246
	v_add_u32_e32 v248, 0x8000, v246
	v_add_u32_e32 v249, 0xc000, v246
	v_lshrrev_b32_e32 v250, 6, v188
	v_lshlrev_b32_e32 v250, 12, v250
	v_readfirstlane_b32 s98, v96
	v_readfirstlane_b32 s99, v97
	v_readfirstlane_b32 s100, v104
	v_readfirstlane_b32 s101, v105
	s_add_u32 s98, s98, s46
	s_addc_u32 s99, s99, s47
	s_add_u32 s100, s100, s46
	s_addc_u32 s101, s101, s47
	s_waitcnt lgkmcnt(0)
	s_barrier

.LBB0_999:
	s_and_b32 s1, s0, 7
	s_mul_i32 s1, s1, s3
	s_ashr_i32 s0, s0, 3
	s_add_i32 s1, s1, s0
	s_mul_hi_i32 s0, s1, 0x2e8ba2e9
	s_lshr_b32 s26, s0, 31
	s_ashr_i32 s0, s0, 6
	s_add_i32 s0, s0, s26
	s_mul_i32 s26, s0, 0x160
	s_sub_i32 s1, s1, s26
	s_lshl_b32 s26, s0, 10
	s_lshl_b32 s0, s1, 7
	s_and_b32 s27, s0, 0x380
	s_lshl_b32 s0, s1, 4
	s_and_b32 s40, s0, 0xffffff80
	s_or_b32 s42, s26, s27
	s_ashr_i32 s41, s40, 31
	s_waitcnt vmcnt(8)
	s_ashr_i32 s43, s42, 31
	s_lshl_b64 s[0:1], s[40:41], 11
	s_lshl_b64 s[26:27], s[42:43], 11
	v_mov_b32_e32 v2, 0
	v_lshl_add_u64 v[94:95], v[70:71], 0, s[26:27]
	v_lshl_add_u64 v[96:97], v[72:73], 0, s[26:27]
	v_lshl_add_u64 v[98:99], v[74:75], 0, s[26:27]
	v_lshl_add_u64 v[100:101], v[76:77], 0, s[26:27]
	v_lshl_add_u64 v[102:103], v[78:79], 0, s[0:1]
	v_lshl_add_u64 v[104:105], v[80:81], 0, s[0:1]
	v_lshl_add_u64 v[106:107], v[82:83], 0, s[0:1]
	v_lshl_add_u64 v[108:109], v[84:85], 0, s[0:1]
	s_mov_b32 s33, 0
	v_mov_b32_e32 v3, v2
	v_mov_b64_e32 v[4:5], v[2:3]
	v_mov_b64_e32 v[6:7], v[2:3]
	v_mov_b64_e32 v[8:9], v[2:3]
	v_mov_b64_e32 v[10:11], v[2:3]
	v_mov_b64_e32 v[12:13], v[2:3]
	v_mov_b64_e32 v[14:15], v[2:3]
	v_mov_b64_e32 v[16:17], v[2:3]
	v_mov_b64_e32 v[18:19], v[2:3]
	v_mov_b64_e32 v[20:21], v[2:3]
	v_mov_b64_e32 v[22:23], v[2:3]
	v_mov_b64_e32 v[24:25], v[2:3]
	v_mov_b64_e32 v[26:27], v[2:3]
	v_mov_b64_e32 v[28:29], v[2:3]
	v_mov_b64_e32 v[30:31], v[2:3]
	v_mov_b64_e32 v[32:33], v[2:3]
	v_mov_b64_e32 v[34:35], v[2:3]
	v_mov_b64_e32 v[36:37], v[2:3]
	v_mov_b64_e32 v[38:39], v[2:3]
	v_mov_b64_e32 v[40:41], v[2:3]
	v_mov_b64_e32 v[42:43], v[2:3]
	v_mov_b64_e32 v[44:45], v[2:3]
	v_mov_b64_e32 v[46:47], v[2:3]
	v_mov_b64_e32 v[48:49], v[2:3]
	v_mov_b64_e32 v[50:51], v[2:3]
	v_mov_b64_e32 v[52:53], v[2:3]
	v_mov_b64_e32 v[54:55], v[2:3]
	v_mov_b64_e32 v[56:57], v[2:3]
	v_mov_b64_e32 v[58:59], v[2:3]
	v_mov_b64_e32 v[60:61], v[2:3]
	v_mov_b64_e32 v[62:63], v[2:3]
	v_mov_b64_e32 v[64:65], v[2:3]
	v_and_b32_e32 v214, 63, v188
	v_lshrrev_b32_e32 v215, 3, v214
	v_and_b32_e32 v216, 7, v214
	v_xor_b32_e32 v216, v216, v215
	v_mul_u32_u24_e32 v246, 0x800, v215
	v_lshl_add_u32 v246, v216, 4, v246
	v_add_u32_e32 v247, 0x4000, v246
	v_add_u32_e32 v248, 0x8000, v246
	v_add_u32_e32 v249, 0xc000, v246
	v_lshrrev_b32_e32 v250, 6, v188
	v_lshlrev_b32_e32 v250, 12, v250
	v_readfirstlane_b32 s98, v94
	v_readfirstlane_b32 s99, v95
	v_readfirstlane_b32 s100, v102
	v_readfirstlane_b32 s101, v103
	s_add_u32 s98, s98, s46
	s_addc_u32 s99, s99, s47
	s_add_u32 s100, s100, s46
	s_addc_u32 s101, s101, s47
	s_waitcnt lgkmcnt(0)
	s_barrier

.LBB0_1057:
	s_and_b32 s1, s0, 7
	s_mul_i32 s1, s1, s2
	s_ashr_i32 s0, s0, 3
	s_add_i32 s0, s1, s0
	s_ashr_i32 s1, s0, 31
	s_lshr_b32 s1, s1, 26
	s_add_i32 s1, s0, s1
	s_and_b32 s19, s1, 0xffffffc0
	s_sub_i32 s0, s0, s19
	s_lshl_b32 s1, s1, 4
	s_lshl_b32 s19, s0, 7
	s_and_b32 s1, s1, 0xfffffc00
	s_and_b32 s19, s19, 0x380
	s_lshl_b32 s0, s0, 4
	s_waitcnt vmcnt(16)
	s_and_b32 s38, s0, 0xffffff80
	s_or_b32 s19, s1, s19
	v_mov_b32_e32 v2, 0
	s_ashr_i32 s39, s38, 31
	v_mad_i64_i32 v[66:67], s[0:1], s19, v208, v[82:83]
	v_mad_i64_i32 v[68:69], s[0:1], s19, v208, v[84:85]
	v_mad_i64_i32 v[100:101], s[0:1], s19, v208, v[86:87]
	v_mad_i64_i32 v[102:103], s[0:1], s19, v208, v[88:89]
	v_mad_i64_i32 v[104:105], s[0:1], s38, v208, v[90:91]
	v_mad_i64_i32 v[106:107], s[0:1], s38, v208, v[92:93]
	v_mad_i64_i32 v[108:109], s[0:1], s38, v208, v[94:95]
	v_mad_i64_i32 v[110:111], s[0:1], s38, v208, v[96:97]
	s_mov_b32 s22, 0
	v_mov_b32_e32 v3, v2
	v_mov_b64_e32 v[4:5], v[2:3]
	v_mov_b64_e32 v[6:7], v[2:3]
	v_mov_b64_e32 v[8:9], v[2:3]
	v_mov_b64_e32 v[10:11], v[2:3]
	v_mov_b64_e32 v[12:13], v[2:3]
	v_mov_b64_e32 v[14:15], v[2:3]
	v_mov_b64_e32 v[16:17], v[2:3]
	v_mov_b64_e32 v[18:19], v[2:3]
	v_mov_b64_e32 v[20:21], v[2:3]
	v_mov_b64_e32 v[22:23], v[2:3]
	v_mov_b64_e32 v[24:25], v[2:3]
	v_mov_b64_e32 v[26:27], v[2:3]
	v_mov_b64_e32 v[28:29], v[2:3]
	v_mov_b64_e32 v[30:31], v[2:3]
	v_mov_b64_e32 v[32:33], v[2:3]
	v_mov_b64_e32 v[34:35], v[2:3]
	v_mov_b64_e32 v[36:37], v[2:3]
	v_mov_b64_e32 v[38:39], v[2:3]
	v_mov_b64_e32 v[40:41], v[2:3]
	v_mov_b64_e32 v[42:43], v[2:3]
	v_mov_b64_e32 v[44:45], v[2:3]
	v_mov_b64_e32 v[46:47], v[2:3]
	v_mov_b64_e32 v[48:49], v[2:3]
	v_mov_b64_e32 v[50:51], v[2:3]
	v_mov_b64_e32 v[52:53], v[2:3]
	v_mov_b64_e32 v[54:55], v[2:3]
	v_mov_b64_e32 v[56:57], v[2:3]
	v_mov_b64_e32 v[58:59], v[2:3]
	v_mov_b64_e32 v[60:61], v[2:3]
	v_mov_b64_e32 v[62:63], v[2:3]
	v_mov_b64_e32 v[64:65], v[2:3]
	s_mov_b32 s24, s25
	v_and_b32_e32 v214, 63, v188
	v_lshrrev_b32_e32 v215, 3, v214
	v_and_b32_e32 v216, 7, v214
	v_xor_b32_e32 v216, v216, v215
	v_mul_u32_u24_e32 v246, 0x1600, v215
	v_lshl_add_u32 v246, v216, 4, v246
	v_add_u32_e32 v247, 0xb000, v246
	v_add_u32_e32 v248, 0x16000, v246
	v_add_u32_e32 v249, 0x21000, v246
	v_lshrrev_b32_e32 v250, 6, v188
	v_lshlrev_b32_e32 v250, 12, v250
	v_readfirstlane_b32 s98, v66
	v_readfirstlane_b32 s99, v67
	v_readfirstlane_b32 s100, v104
	v_readfirstlane_b32 s101, v105
	s_add_u32 s98, s98, s42
	s_addc_u32 s99, s99, s43
	s_add_u32 s100, s100, s42
	s_addc_u32 s101, s101, s43
	s_waitcnt vmcnt(16) lgkmcnt(0)
	s_barrier
